# best_v1 + SO2: hand-written S4 stage of the scan (frame scaling): fused f16 mix ops, immediate-offset LDS stores, batched reads
# speedup vs baseline: 1.0240x; 1.0067x over previous
.LBB0_387:
	s_or_b64 exec, exec, s[16:17]
	v_cndmask_b32_e32 v38, 0, v38, vcc
	v_cndmask_b32_e64 v50, 0, v50, s[10:11]
	v_and_b32_e32 v93, 0xffff0000, v46
	v_lshlrev_b32_e32 v99, 16, v46
	v_and_b32_e32 v46, 0xffff0000, v38
	v_and_b32_e32 v100, 0xffff0000, v50
	v_lshlrev_b32_e32 v38, 16, v38
	v_lshlrev_b32_e32 v50, 16, v50
	v_cndmask_b32_e32 v39, 0, v39, vcc
	v_cndmask_b32_e64 v51, 0, v51, s[10:11]
	v_add_f32_e32 v46, v46, v100
	v_add_f32_e32 v38, v38, v50
	v_fma_f32 v100, v38, 0.5, -v99
	v_fma_f32 v101, v46, 0.5, -v93
	v_and_b32_e32 v38, 0xffff0000, v39
	v_and_b32_e32 v46, 0xffff0000, v51
	v_add_f32_e32 v38, v38, v46
	v_lshlrev_b32_e32 v39, 16, v39
	v_lshlrev_b32_e32 v46, 16, v51
	v_cndmask_b32_e32 v40, 0, v40, vcc
	v_cndmask_b32_e64 v52, 0, v52, s[10:11]
	v_and_b32_e32 v106, 0xffff0000, v47
	v_lshlrev_b32_e32 v127, 16, v47
	v_add_f32_e32 v39, v39, v46
	v_fma_f32 v51, v39, 0.5, -v127
	v_fma_f32 v130, v38, 0.5, -v106
	v_and_b32_e32 v38, 0xffff0000, v40
	v_and_b32_e32 v39, 0xffff0000, v52
	v_add_f32_e32 v46, v97, v98
	v_add_f32_e32 v38, v38, v39
	v_lshlrev_b32_e32 v39, 16, v40
	v_lshlrev_b32_e32 v40, 16, v52
	v_sqrt_f32_e32 v50, v46
	v_cndmask_b32_e32 v41, 0, v41, vcc
	v_cndmask_b32_e64 v53, 0, v53, s[10:11]
	v_and_b32_e32 v131, 0xffff0000, v48
	v_lshlrev_b32_e32 v132, 16, v48
	v_add_f32_e32 v39, v39, v40
	v_fma_f32 v52, v39, 0.5, -v132
	v_fma_f32 v133, v38, 0.5, -v131
	v_and_b32_e32 v38, 0xffff0000, v41
	v_and_b32_e32 v39, 0xffff0000, v53
	v_add_f32_e32 v38, v38, v39
	v_lshlrev_b32_e32 v39, 16, v41
	v_lshlrev_b32_e32 v40, 16, v53
	v_and_b32_e32 v134, 0xffff0000, v49
	v_lshlrev_b32_e32 v135, 16, v49
	v_add_f32_e32 v39, v39, v40
	v_max_f32_e32 v50, 0x2b8cbccc, v50
	v_fma_f32 v53, v39, 0.5, -v135
	v_fma_f32 v136, v38, 0.5, -v134
	v_cvt_f32_f16_sdwa v39, v54 dst_sel:DWORD dst_unused:UNUSED_PAD src0_sel:WORD_1
	v_cvt_f32_f16_e32 v38, v54
	v_cvt_f32_f16_sdwa v41, v55 dst_sel:DWORD dst_unused:UNUSED_PAD src0_sel:WORD_1
	v_cvt_f32_f16_e32 v40, v55
	v_rcp_f32_e32 v50, v50
	v_cvt_f32_f16_sdwa v47, v56 dst_sel:DWORD dst_unused:UNUSED_PAD src0_sel:WORD_1
	v_cvt_f32_f16_e32 v46, v56
	v_cvt_f32_f16_sdwa v49, v57 dst_sel:DWORD dst_unused:UNUSED_PAD src0_sel:WORD_1
	v_cvt_f32_f16_e32 v48, v57
	v_add_u32_e32 v54, v95, v96
	ds_write_b128 v54, v[38:41] offset:34816
	ds_write_b128 v54, v[46:49] offset:34832
	v_pk_mul_f32 v[38:39], v[66:67], v[50:51] op_sel_hi:[1,0]
	v_pk_mul_f32 v[40:41], v[80:81], v[50:51] op_sel_hi:[1,0]
	v_cvt_pk_f16_f32 v38, v38, v39
	v_cvt_pk_f16_f32 v39, v40, v41
	v_pk_mul_f32 v[40:41], v[84:85], v[50:51] op_sel_hi:[1,0]
	v_pk_mul_f32 v[46:47], v[86:87], v[50:51] op_sel_hi:[1,0]
	v_cvt_pk_f16_f32 v40, v40, v41
	v_cvt_pk_f16_f32 v41, v46, v47
	ds_write_b128 v95, v[38:41] offset:51200
	v_pk_mul_f32 v[38:39], v[66:67], v[50:51] op_sel_hi:[1,0] neg_lo:[0,1] neg_hi:[0,1]
	v_pk_mul_f32 v[40:41], v[80:81], v[50:51] op_sel_hi:[1,0] neg_lo:[0,1] neg_hi:[0,1]
	v_pk_mul_f32 v[38:39], v[38:39], v[68:69]
	v_pk_mul_f32 v[40:41], v[40:41], v[78:79]
	v_cvt_pk_f16_f32 v38, v38, v39
	v_cvt_pk_f16_f32 v39, v40, v41
	v_pk_mul_f32 v[40:41], v[84:85], v[50:51] op_sel_hi:[1,0] neg_lo:[0,1] neg_hi:[0,1]
	v_pk_mul_f32 v[46:47], v[86:87], v[50:51] op_sel_hi:[1,0] neg_lo:[0,1] neg_hi:[0,1]
	v_pk_mul_f32 v[40:41], v[40:41], v[82:83]
	v_pk_mul_f32 v[46:47], v[46:47], v[88:89]
	v_cvt_pk_f16_f32 v40, v40, v41
	v_cvt_pk_f16_f32 v41, v46, v47
	ds_write_b128 v95, v[38:41] offset:59392
	v_cvt_pk_f16_f32 v38, v74, v75
	v_cvt_pk_f16_f32 v39, v76, v77
	v_cvt_pk_f16_f32 v40, v72, v73
	v_cvt_pk_f16_f32 v41, v70, v71
	v_add_u32_e32 v46, 0x10800, v95
	ds_write_b128 v46, v[38:41]
	v_cvt_pk_f16_f32 v38, v58, v59
	v_cvt_pk_f16_f32 v39, v60, v61
	v_cvt_pk_f16_f32 v40, v62, v63
	v_cvt_pk_f16_f32 v41, v64, v65
	v_add_u32_e32 v46, 0x12800, v95
	ds_write_b128 v46, v[38:41]
	v_lshlrev_b32_e32 v38, 7, v94
	v_lshlrev_b32_e32 v39, 8, v91
	v_and_b32_e32 v38, 0xfffff800, v38
	s_add_i32 s10, 0, 0x18800
	v_and_b32_e32 v39, 0x400, v39
	v_lshlrev_b32_e32 v40, 8, v90
	v_add3_u32 v38, s10, v38, v39
	v_lshlrev_b32_e32 v39, 2, v92
	v_and_b32_e32 v40, 0x300, v40
	v_and_b32_e32 v39, 16, v39
	v_add3_u32 v38, v38, v40, v39
	v_lshlrev_b32_e32 v39, 1, v92
	v_and_b32_e32 v39, 6, v39
	v_and_b32_e32 v40, 8, v94
	v_add3_u32 v38, v38, v40, v39
	v_fma_mixlo_f16 v34, v34, v52, v132
	v_fma_mixlo_f16 v39, v42, v100, v99
	ds_write_b16 v38, v34 offset:128
	v_fma_mixlo_f16 v34, v35, v133, v131
	ds_write_b16 v38, v39
	v_fma_mixlo_f16 v39, v43, v101, v93
	ds_write_b16 v38, v34 offset:160
	v_fma_mixlo_f16 v34, v36, v53, v135
	ds_write_b16 v38, v39 offset:32
	v_fma_mixlo_f16 v39, v44, v51, v127
	ds_write_b16 v38, v34 offset:192
	v_fma_mixlo_f16 v34, v136, v37, v134
	v_lshlrev_b32_e32 v44, 2, v90
	ds_write_b16 v38, v39 offset:64
	v_fma_mixlo_f16 v39, v45, v130, v106
	ds_write_b16 v38, v34 offset:224
	v_lshlrev_b32_e32 v34, 1, v90
	v_add_u32_e32 v43, s75, v44
	ds_write_b16 v38, v39 offset:96
	s_waitcnt lgkmcnt(0)
	s_barrier
	v_and_b32_e32 v46, 6, v34
	ds_read2st64_b32 v[34:35], v43 offset0:136 offset1:137
	ds_read2st64_b32 v[36:37], v43 offset0:138 offset1:139
	ds_read2st64_b32 v[38:39], v43 offset0:140 offset1:141
	ds_read2st64_b32 v[40:41], v43 offset0:142 offset1:143
	v_ashrrev_i32_e32 v42, 4, v90
	v_and_b32_e32 v48, 8, v90
	s_movk_i32 s14, 0x3c0
	s_waitcnt lgkmcnt(3)
	v_add_f32_e32 v68, 0, v34
	v_add_f32_e32 v65, v68, v35
	s_waitcnt lgkmcnt(2)
	v_add_f32_e32 v63, v65, v36
	v_add_f32_e32 v61, v63, v37
	ds_read2st64_b32 v[34:35], v43 offset0:144 offset1:145
	s_waitcnt lgkmcnt(2)
	v_add_f32_e32 v59, v61, v38
	v_add_f32_e32 v57, v59, v39
	s_waitcnt lgkmcnt(1)
	v_add_f32_e32 v53, v57, v40
	v_add_f32_e32 v36, v53, v41
	ds_read2st64_b32 v[38:39], v43 offset0:146 offset1:147
	ds_read2st64_b32 v[40:41], v43 offset0:148 offset1:149
	ds_read2st64_b32 v[54:55], v43 offset0:150 offset1:151
	s_waitcnt lgkmcnt(3)
	v_add_f32_e32 v51, v36, v34
	v_add_f32_e32 v49, v51, v35
	s_waitcnt lgkmcnt(2)
	v_add_f32_e32 v47, v49, v38
	v_add_f32_e32 v45, v47, v39
	s_waitcnt lgkmcnt(1)
	v_add_f32_e32 v43, v45, v40
	v_add_f32_e32 v41, v43, v41
	v_and_b32_e32 v34, 16, v44
	s_waitcnt lgkmcnt(0)
	v_add_f32_e32 v39, v41, v54
	v_or3_b32 v34, v46, v48, v34
	v_lshlrev_b32_e32 v35, 10, v42
	v_add_u32_e32 v37, s77, v90
	v_lshlrev_b32_e32 v38, 6, v42
	v_sub_f32_e32 v40, v36, v36
	v_and_b32_e32 v128, 31, v90
	v_ashrrev_i32_e32 v125, 5, v90
	v_add_f32_e32 v66, v39, v55
	s_mov_b64 s[10:11], -1
	s_and_b64 vcc, exec, s[88:89]
	v_add3_u32 v34, s75, v35, v34
	v_xor_b32_e32 v35, 0x200, v38
	v_lshl_add_u32 v37, v37, 1, 0
	v_and_b32_e32 v70, 0x3c0, v38
	v_bitop3_b32 v69, v38, s14, v214 bitop3:0x48
	v_add_u32_e32 v64, 64, v38
	v_add_u32_e32 v62, 0x60, v38
	v_add_u32_e32 v60, 0x80, v38
	v_add_u32_e32 v58, 0xa0, v38
	v_add_u32_e32 v56, 0xc0, v38
	v_mul_f32_e32 v55, 0x3fb8aa3b, v40
	v_add_u32_e32 v54, 0xe0, v38
	v_add_u32_e32 v52, 0x100, v38
	v_add_u32_e32 v50, 0x120, v38
	v_add_u32_e32 v48, 0x140, v38
	v_add_u32_e32 v46, 0x160, v38
	v_add_u32_e32 v44, 0x180, v38
	v_add_u32_e32 v42, 0x1a0, v38
	v_add_u32_e32 v40, 0x1c0, v38
	v_add_u32_e32 v38, 0x1e0, v38
	s_cbranch_vccz .LBB0_389
	s_movk_i32 s32, 0x3e0
	v_add_u32_e32 v48, 0x10800, v37
	v_mov_b32_e32 v62, v70
	v_add_u32_e32 v50, v34, v70
	ds_read_u16 v69, v37 offset:59392
	ds_read_u16 v70, v48 offset:0
	ds_read_u16 v71, v37 offset:59520
	ds_read_u16 v72, v48 offset:128
	ds_read_u16 v73, v37 offset:59648
	ds_read_u16 v74, v48 offset:256
	ds_read_u16 v75, v37 offset:59776
	ds_read_u16 v76, v48 offset:384
	ds_read_u16 v77, v37 offset:59904
	ds_read_u16 v78, v48 offset:512
	ds_read_u16 v79, v37 offset:60032
	ds_read_u16 v88, v48 offset:640
	v_sub_f32_e32 v52, v36, v68
	v_mul_f32_e32 v52, 0x3fb8aa3b, v52
	v_exp_f32_e32 v52, v52
	ds_read_u16 v89, v37 offset:60160
	ds_read_u16 v91, v48 offset:768
	s_waitcnt lgkmcnt(13)
	v_fma_mix_f32 v40, v52, v69, 0 op_sel_hi:[0,1,0]
	s_waitcnt lgkmcnt(12)
	v_fma_mix_f32 v44, v52, v70, 0 op_sel_hi:[0,1,0]
	v_sub_f32_e32 v54, v36, v65
	v_mul_f32_e32 v54, 0x3fb8aa3b, v54
	v_exp_f32_e32 v54, v54
	ds_read_u16 v100, v37 offset:60288
	ds_read_u16 v101, v48 offset:896
	s_waitcnt lgkmcnt(13)
	v_fma_mix_f32 v42, v54, v71, 0 op_sel_hi:[0,1,0]
	s_waitcnt lgkmcnt(12)
	v_fma_mix_f32 v46, v54, v72, 0 op_sel_hi:[0,1,0]
	v_cvt_pk_f16_f32 v92, v40, v42
	v_cvt_pk_f16_f32 v80, v44, v46
	ds_write_b16 v50, v92 offset:16384
	ds_write_b16_d16_hi v50, v92 offset:16416
	s_waitcnt lgkmcnt(8)
	ds_write_b16 v50, v80 offset:16896
	ds_write_b16_d16_hi v50, v80 offset:16928
	v_sub_f32_e32 v52, v36, v63
	v_mul_f32_e32 v52, 0x3fb8aa3b, v52
	v_exp_f32_e32 v52, v52
	ds_read_u16 v69, v37 offset:60416
	ds_read_u16 v70, v48 offset:1024
	v_fma_mix_f32 v40, v52, v73, 0 op_sel_hi:[0,1,0]
	v_fma_mix_f32 v44, v52, v74, 0 op_sel_hi:[0,1,0]
	v_sub_f32_e32 v54, v36, v61
	v_mul_f32_e32 v54, 0x3fb8aa3b, v54
	v_exp_f32_e32 v54, v54
	ds_read_u16 v71, v37 offset:60544
	ds_read_u16 v72, v48 offset:1152
	v_fma_mix_f32 v42, v54, v75, 0 op_sel_hi:[0,1,0]
	v_fma_mix_f32 v46, v54, v76, 0 op_sel_hi:[0,1,0]
	v_cvt_pk_f16_f32 v93, v40, v42
	v_cvt_pk_f16_f32 v81, v44, v46
	s_waitcnt lgkmcnt(8)
	ds_write_b16 v50, v93 offset:16448
	ds_write_b16_d16_hi v50, v93 offset:16480
	ds_write_b16 v50, v81 offset:16960
	ds_write_b16_d16_hi v50, v81 offset:16992
	v_sub_f32_e32 v52, v36, v59
	v_mul_f32_e32 v52, 0x3fb8aa3b, v52
	v_exp_f32_e32 v52, v52
	ds_read_u16 v73, v37 offset:60672
	ds_read_u16 v74, v48 offset:1280
	v_fma_mix_f32 v40, v52, v77, 0 op_sel_hi:[0,1,0]
	v_fma_mix_f32 v44, v52, v78, 0 op_sel_hi:[0,1,0]
	v_sub_f32_e32 v54, v36, v57
	v_mul_f32_e32 v54, 0x3fb8aa3b, v54
	v_exp_f32_e32 v54, v54
	s_waitcnt lgkmcnt(8)
	ds_read_u16 v75, v37 offset:60800
	ds_read_u16 v76, v48 offset:1408
	v_fma_mix_f32 v42, v54, v79, 0 op_sel_hi:[0,1,0]
	v_fma_mix_f32 v46, v54, v88, 0 op_sel_hi:[0,1,0]
	v_cvt_pk_f16_f32 v96, v40, v42
	v_cvt_pk_f16_f32 v84, v44, v46
	ds_write_b16 v50, v96 offset:16512
	ds_write_b16_d16_hi v50, v96 offset:16544
	ds_write_b16 v50, v84 offset:17024
	ds_write_b16_d16_hi v50, v84 offset:17056
	v_sub_f32_e32 v52, v36, v53
	v_mul_f32_e32 v52, 0x3fb8aa3b, v52
	v_exp_f32_e32 v52, v52
	s_waitcnt lgkmcnt(8)
	ds_read_u16 v77, v37 offset:60928
	ds_read_u16 v78, v48 offset:1536
	v_fma_mix_f32 v40, v52, v89, 0 op_sel_hi:[0,1,0]
	v_fma_mix_f32 v44, v52, v91, 0 op_sel_hi:[0,1,0]
	v_cvt_f32_f16_e32 v42, v100
	v_cvt_f32_f16_e32 v46, v101
	ds_read_u16 v79, v37 offset:61056
	ds_read_u16 v88, v48 offset:1664
	v_cvt_pk_f16_f32 v97, v40, v42
	v_cvt_pk_f16_f32 v85, v44, v46
	ds_write_b16 v50, v97 offset:16576
	ds_write_b16_d16_hi v50, v97 offset:16608
	s_waitcnt lgkmcnt(8)
	ds_write_b16 v50, v85 offset:17088
	ds_write_b16_d16_hi v50, v85 offset:17120
	v_sub_f32_e32 v52, v36, v51
	v_mul_f32_e32 v52, 0x3fb8aa3b, v52
	v_exp_f32_e32 v52, v52
	ds_read_u16 v89, v37 offset:61184
	ds_read_u16 v91, v48 offset:1792
	v_fma_mix_f32 v40, v52, v69, 0 op_sel_hi:[0,1,0]
	v_fma_mix_f32 v44, v52, v70, 0 op_sel_hi:[0,1,0]
	v_sub_f32_e32 v54, v36, v49
	v_mul_f32_e32 v54, 0x3fb8aa3b, v54
	v_exp_f32_e32 v54, v54
	ds_read_u16 v100, v37 offset:61312
	ds_read_u16 v101, v48 offset:1920
	v_fma_mix_f32 v42, v54, v71, 0 op_sel_hi:[0,1,0]
	v_fma_mix_f32 v46, v54, v72, 0 op_sel_hi:[0,1,0]
	v_cvt_pk_f16_f32 v94, v40, v42
	v_cvt_pk_f16_f32 v82, v44, v46
	s_waitcnt lgkmcnt(8)
	ds_write_b16 v50, v94 offset:16640
	ds_write_b16_d16_hi v50, v94 offset:16672
	ds_write_b16 v50, v82 offset:17152
	ds_write_b16_d16_hi v50, v82 offset:17184
	v_sub_f32_e32 v52, v36, v47
	v_mul_f32_e32 v52, 0x3fb8aa3b, v52
	v_exp_f32_e32 v52, v52
	s_nop 0
	v_fma_mix_f32 v40, v52, v73, 0 op_sel_hi:[0,1,0]
	v_fma_mix_f32 v44, v52, v74, 0 op_sel_hi:[0,1,0]
	v_sub_f32_e32 v54, v36, v45
	v_mul_f32_e32 v54, 0x3fb8aa3b, v54
	v_exp_f32_e32 v54, v54
	s_nop 0
	v_fma_mix_f32 v42, v54, v75, 0 op_sel_hi:[0,1,0]
	v_fma_mix_f32 v46, v54, v76, 0 op_sel_hi:[0,1,0]
	v_cvt_pk_f16_f32 v95, v40, v42
	v_cvt_pk_f16_f32 v83, v44, v46
	ds_write_b16 v50, v95 offset:16704
	ds_write_b16_d16_hi v50, v95 offset:16736
	v_add_u32_e32 v56, 0x340, v62
	v_and_or_b32 v56, v56, s32, v34
	s_waitcnt lgkmcnt(8)
	ds_write_b16 v56, v83 offset:16384
	ds_write_b16_d16_hi v56, v83 offset:16416
	v_sub_f32_e32 v52, v36, v43
	v_mul_f32_e32 v52, 0x3fb8aa3b, v52
	v_exp_f32_e32 v52, v52
	s_nop 0
	v_fma_mix_f32 v40, v52, v77, 0 op_sel_hi:[0,1,0]
	v_fma_mix_f32 v44, v52, v78, 0 op_sel_hi:[0,1,0]
	v_sub_f32_e32 v54, v36, v41
	v_mul_f32_e32 v54, 0x3fb8aa3b, v54
	v_exp_f32_e32 v54, v54
	s_nop 0
	v_fma_mix_f32 v42, v54, v79, 0 op_sel_hi:[0,1,0]
	v_fma_mix_f32 v46, v54, v88, 0 op_sel_hi:[0,1,0]
	v_cvt_pk_f16_f32 v98, v40, v42
	v_cvt_pk_f16_f32 v86, v44, v46
	ds_write_b16 v50, v98 offset:16768
	ds_write_b16_d16_hi v50, v98 offset:16800
	v_add_u32_e32 v56, 0x380, v62
	v_and_or_b32 v56, v56, s32, v34
	ds_write_b16 v56, v86 offset:16384
	ds_write_b16_d16_hi v56, v86 offset:16416
	v_sub_f32_e32 v52, v36, v39
	v_mul_f32_e32 v52, 0x3fb8aa3b, v52
	v_exp_f32_e32 v52, v52
	s_nop 0
	v_fma_mix_f32 v40, v52, v89, 0 op_sel_hi:[0,1,0]
	v_fma_mix_f32 v44, v52, v91, 0 op_sel_hi:[0,1,0]
	v_sub_f32_e32 v54, v36, v66
	v_mul_f32_e32 v54, 0x3fb8aa3b, v54
	v_exp_f32_e32 v54, v54
	s_waitcnt lgkmcnt(13)
	v_fma_mix_f32 v42, v54, v100, 0 op_sel_hi:[0,1,0]
	s_waitcnt lgkmcnt(12)
	v_fma_mix_f32 v46, v54, v101, 0 op_sel_hi:[0,1,0]
	v_cvt_pk_f16_f32 v99, v40, v42
	v_cvt_pk_f16_f32 v87, v44, v46
	ds_write_b16 v50, v99 offset:16832
	ds_write_b16_d16_hi v50, v99 offset:16864
	v_add_u32_e32 v56, 0x3c0, v62
	v_and_or_b32 v56, v56, s32, v34
	s_waitcnt lgkmcnt(8)
	ds_write_b16 v56, v87 offset:16384
	ds_write_b16_d16_hi v56, v87 offset:16416
	v_lshlrev_b32_e32 v58, 11, v125
	v_lshlrev_b32_e32 v60, 5, v128
	v_add3_u32 v58, s76, v58, v60
	ds_write_b128 v58, v[92:95]
	ds_write_b128 v58, v[96:99] offset:16
	ds_write_b128 v58, v[80:83] offset:1024
	ds_write_b128 v58, v[84:87] offset:1040
	s_mov_b64 s[10:11], 0
.LBB0_389:
	s_andn2_b64 vcc, exec, s[10:11]
	s_cbranch_vccnz .LBB0_391
	s_movk_i32 s32, 0x3e0
	v_add_u32_e32 v48, 0x12800, v37
	v_mov_b32_e32 v62, v70
	v_add_u32_e32 v50, v34, v70
	ds_read_u16 v69, v37 offset:51200
	ds_read_u16 v70, v48 offset:0
	ds_read_u16 v71, v37 offset:51328
	ds_read_u16 v72, v48 offset:128
	ds_read_u16 v73, v37 offset:51456
	ds_read_u16 v74, v48 offset:256
	ds_read_u16 v75, v37 offset:51584
	ds_read_u16 v76, v48 offset:384
	ds_read_u16 v77, v37 offset:51712
	ds_read_u16 v78, v48 offset:512
	ds_read_u16 v79, v37 offset:51840
	ds_read_u16 v88, v48 offset:640
	v_mul_f32_e32 v84, 0xbfb8aa3b, v36
	v_exp_f32_e32 v84, v84
	v_mul_f32_e32 v85, 0x3fb8aa3b, v36
	v_exp_f32_e32 v85, v85
	v_sub_f32_e32 v80, v68, v36
	v_mul_f32_e32 v80, 0x3fb8aa3b, v80
	v_exp_f32_e32 v80, v80
	ds_read_u16 v89, v37 offset:51968
	ds_read_u16 v91, v48 offset:768
	s_waitcnt lgkmcnt(13)
	v_fma_mixlo_f16 v40, v84, v69, 0 op_sel_hi:[0,1,0]
	s_waitcnt lgkmcnt(12)
	v_fma_mixlo_f16 v42, v80, v70, 0 op_sel_hi:[0,1,0]
	ds_write_b16 v50, v40 offset:0
	ds_write_b16 v50, v42 offset:512
	v_sub_f32_e32 v81, v65, v36
	v_mul_f32_e32 v81, 0x3fb8aa3b, v81
	v_exp_f32_e32 v81, v81
	s_waitcnt lgkmcnt(8)
	ds_read_u16 v100, v37 offset:52096
	ds_read_u16 v101, v48 offset:896
	v_fma_mixlo_f16 v44, v80, v71, 0 op_sel_hi:[0,1,0]
	v_fma_mixlo_f16 v46, v81, v72, 0 op_sel_hi:[0,1,0]
	ds_write_b16 v50, v44 offset:32
	ds_write_b16 v50, v46 offset:544
	v_sub_f32_e32 v82, v63, v36
	v_mul_f32_e32 v82, 0x3fb8aa3b, v82
	v_exp_f32_e32 v82, v82
	ds_read_u16 v69, v37 offset:52224
	ds_read_u16 v70, v48 offset:1024
	v_fma_mixlo_f16 v40, v81, v73, 0 op_sel_hi:[0,1,0]
	v_fma_mixlo_f16 v42, v82, v74, 0 op_sel_hi:[0,1,0]
	s_waitcnt lgkmcnt(8)
	ds_write_b16 v50, v40 offset:64
	ds_write_b16 v50, v42 offset:576
	v_sub_f32_e32 v83, v61, v36
	v_mul_f32_e32 v83, 0x3fb8aa3b, v83
	v_exp_f32_e32 v83, v83
	ds_read_u16 v71, v37 offset:52352
	ds_read_u16 v72, v48 offset:1152
	v_fma_mixlo_f16 v44, v82, v75, 0 op_sel_hi:[0,1,0]
	v_fma_mixlo_f16 v46, v83, v76, 0 op_sel_hi:[0,1,0]
	ds_write_b16 v50, v44 offset:96
	ds_write_b16 v50, v46 offset:608
	v_sub_f32_e32 v80, v59, v36
	v_mul_f32_e32 v80, 0x3fb8aa3b, v80
	v_exp_f32_e32 v80, v80
	s_waitcnt lgkmcnt(8)
	ds_read_u16 v73, v37 offset:52480
	ds_read_u16 v74, v48 offset:1280
	v_fma_mixlo_f16 v40, v83, v77, 0 op_sel_hi:[0,1,0]
	v_fma_mixlo_f16 v42, v80, v78, 0 op_sel_hi:[0,1,0]
	ds_write_b16 v50, v40 offset:128
	ds_write_b16 v50, v42 offset:640
	v_sub_f32_e32 v81, v57, v36
	v_mul_f32_e32 v81, 0x3fb8aa3b, v81
	v_exp_f32_e32 v81, v81
	ds_read_u16 v75, v37 offset:52608
	ds_read_u16 v76, v48 offset:1408
	v_fma_mixlo_f16 v44, v80, v79, 0 op_sel_hi:[0,1,0]
	v_fma_mixlo_f16 v46, v81, v88, 0 op_sel_hi:[0,1,0]
	s_waitcnt lgkmcnt(8)
	ds_write_b16 v50, v44 offset:160
	ds_write_b16 v50, v46 offset:672
	v_sub_f32_e32 v82, v53, v36
	v_mul_f32_e32 v82, 0x3fb8aa3b, v82
	v_exp_f32_e32 v82, v82
	ds_read_u16 v77, v37 offset:52736
	ds_read_u16 v78, v48 offset:1536
	v_fma_mixlo_f16 v40, v81, v89, 0 op_sel_hi:[0,1,0]
	v_fma_mixlo_f16 v42, v82, v91, 0 op_sel_hi:[0,1,0]
	ds_write_b16 v50, v40 offset:192
	ds_write_b16 v50, v42 offset:704
	v_mov_b32_e32 v83, 1.0
	s_waitcnt lgkmcnt(8)
	ds_read_u16 v79, v37 offset:52864
	ds_read_u16 v88, v48 offset:1664
	v_fma_mixlo_f16 v44, v82, v100, 0 op_sel_hi:[0,1,0]
	v_fma_mixlo_f16 v46, v83, v101, 0 op_sel_hi:[0,1,0]
	ds_write_b16 v50, v44 offset:224
	ds_write_b16 v50, v46 offset:736
	v_sub_f32_e32 v80, v51, v36
	v_mul_f32_e32 v80, 0x3fb8aa3b, v80
	v_exp_f32_e32 v80, v80
	ds_read_u16 v89, v37 offset:52992
	ds_read_u16 v91, v48 offset:1792
	v_fma_mixlo_f16 v40, v83, v69, 0 op_sel_hi:[0,1,0]
	v_fma_mixlo_f16 v42, v80, v70, 0 op_sel_hi:[0,1,0]
	s_waitcnt lgkmcnt(8)
	ds_write_b16 v50, v40 offset:256
	ds_write_b16 v50, v42 offset:768
	v_sub_f32_e32 v81, v49, v36
	v_mul_f32_e32 v81, 0x3fb8aa3b, v81
	v_exp_f32_e32 v81, v81
	ds_read_u16 v100, v37 offset:53120
	ds_read_u16 v101, v48 offset:1920
	v_fma_mixlo_f16 v44, v80, v71, 0 op_sel_hi:[0,1,0]
	v_fma_mixlo_f16 v46, v81, v72, 0 op_sel_hi:[0,1,0]
	ds_write_b16 v50, v44 offset:288
	ds_write_b16 v50, v46 offset:800
	v_sub_f32_e32 v82, v47, v36
	v_mul_f32_e32 v82, 0x3fb8aa3b, v82
	v_exp_f32_e32 v82, v82
	v_fma_mixlo_f16 v40, v81, v73, 0 op_sel_hi:[0,1,0]
	v_fma_mixlo_f16 v42, v82, v74, 0 op_sel_hi:[0,1,0]
	s_waitcnt lgkmcnt(8)
	ds_write_b16 v50, v40 offset:320
	v_add_u32_e32 v56, 0x340, v62
	v_and_or_b32 v56, v56, s32, v34
	ds_write_b16 v56, v42
	v_sub_f32_e32 v83, v45, v36
	v_mul_f32_e32 v83, 0x3fb8aa3b, v83
	v_exp_f32_e32 v83, v83
	v_fma_mixlo_f16 v44, v82, v75, 0 op_sel_hi:[0,1,0]
	v_fma_mixlo_f16 v46, v83, v76, 0 op_sel_hi:[0,1,0]
	ds_write_b16 v50, v44 offset:352
	ds_write_b16 v56, v46 offset:32
	v_sub_f32_e32 v80, v43, v36
	v_mul_f32_e32 v80, 0x3fb8aa3b, v80
	v_exp_f32_e32 v80, v80
	v_fma_mixlo_f16 v40, v83, v77, 0 op_sel_hi:[0,1,0]
	v_fma_mixlo_f16 v42, v80, v78, 0 op_sel_hi:[0,1,0]
	ds_write_b16 v50, v40 offset:384
	v_add_u32_e32 v56, 0x380, v62
	v_and_or_b32 v56, v56, s32, v34
	ds_write_b16 v56, v42
	v_sub_f32_e32 v81, v41, v36
	v_mul_f32_e32 v81, 0x3fb8aa3b, v81
	v_exp_f32_e32 v81, v81
	v_fma_mixlo_f16 v44, v80, v79, 0 op_sel_hi:[0,1,0]
	v_fma_mixlo_f16 v46, v81, v88, 0 op_sel_hi:[0,1,0]
	s_waitcnt lgkmcnt(8)
	ds_write_b16 v50, v44 offset:416
	ds_write_b16 v56, v46 offset:32
	v_sub_f32_e32 v82, v39, v36
	v_mul_f32_e32 v82, 0x3fb8aa3b, v82
	v_exp_f32_e32 v82, v82
	v_fma_mixlo_f16 v40, v81, v89, 0 op_sel_hi:[0,1,0]
	v_fma_mixlo_f16 v42, v82, v91, 0 op_sel_hi:[0,1,0]
	ds_write_b16 v50, v40 offset:448
	v_add_u32_e32 v56, 0x3c0, v62
	v_and_or_b32 v56, v56, s32, v34
	ds_write_b16 v56, v42
	v_sub_f32_e32 v83, v66, v36
	v_mul_f32_e32 v83, 0x3fb8aa3b, v83
	v_exp_f32_e32 v83, v83
	v_fma_mixlo_f16 v44, v82, v100, 0 op_sel_hi:[0,1,0]
	v_fma_mixlo_f16 v46, v83, v101, 0 op_sel_hi:[0,1,0]
	ds_write_b16 v50, v44 offset:480
	ds_write_b16 v56, v46 offset:32
	v_lshl_add_u32 v58, v90, 2, s62
	s_waitcnt lgkmcnt(8)
	ds_write2st64_b32 v58, v85, v83 offset1:1
